# P9 cross-attention scores: q fragment loads issued one step ahead (4-step K-chunk loop unrolled)
# baseline (speedup 1.0000x reference)
; #define LAS __attribute__((address_space(3)))
; #define MFMA32(a, b, c) __builtin_amdgcn_mfma_f32_32x32x16_bf16((a), (b), (c), 0, 0, 0)
; __device__ __forceinline__ void xa_item(int it, LAS unsigned char* lds, const bf16_t* XQ, const bf16_t* XK, bf16_t* PB, int tid, int wid, int lane) {
;     ...
;         if (wid < 4) {
; #pragma unroll 2
;             for (int ks = 0; ks < 8; ++ks) {
;                 const bf16x8 qv = *(const bf16x8*)(qp + c * 128 + 16 * ks);
; #pragma unroll
;                 for (int mt = 0; mt < 8; ++mt) st[mt] = MFMA32(*(const LAS bf16x8*)(KL + (32 * mt + x) * KS + 16 * ks + 8 * hi), qv, st[mt]);
;             }
;         }
.LBB0_1517:
	global_load_dwordx4 v[6:9], v[4:5], off offset:-32
	global_load_dwordx4 v[10:13], v[4:5], off
	s_mov_b32 s6, 0
	global_load_dwordx4 v[230:233], v[4:5], off offset:32
	global_load_dwordx4 v[234:237], v[4:5], off offset:64
	v_add_u32_e32 v3, s6, v195
	ds_read_b128 v[14:17], v3
	ds_read_b128 v[198:201], v3 offset:32
	v_add_u32_e32 v185, s6, v194
	v_add_u32_e32 v210, s6, v193
	v_add_u32_e32 v218, s6, v192
	v_add_u32_e32 v226, s6, v191
	s_waitcnt vmcnt(3) lgkmcnt(1)
	v_mfma_f32_32x32x16_bf16 v[130:145], v[14:17], v[6:9], v[130:145]
	ds_read_b128 v[14:17], v185
	ds_read_b128 v[202:205], v185 offset:32
	s_waitcnt lgkmcnt(1)
	v_mfma_f32_32x32x16_bf16 v[114:129], v[14:17], v[6:9], v[114:129]
	ds_read_b128 v[14:17], v3 offset:17408
	ds_read_b128 v[206:209], v3 offset:17440
	s_waitcnt lgkmcnt(1)
	v_mfma_f32_32x32x16_bf16 v[98:113], v[14:17], v[6:9], v[98:113]
	ds_read_b128 v[14:17], v210
	ds_read_b128 v[210:213], v210 offset:32
	s_waitcnt lgkmcnt(1)
	v_mfma_f32_32x32x16_bf16 v[82:97], v[14:17], v[6:9], v[82:97]
	ds_read_b128 v[14:17], v3 offset:34816
	ds_read_b128 v[214:217], v3 offset:34848
	s_waitcnt lgkmcnt(1)
	v_mfma_f32_32x32x16_bf16 v[66:81], v[14:17], v[6:9], v[66:81]
	ds_read_b128 v[14:17], v218
	ds_read_b128 v[218:221], v218 offset:32
	s_waitcnt lgkmcnt(1)
	v_mfma_f32_32x32x16_bf16 v[50:65], v[14:17], v[6:9], v[50:65]
	ds_read_b128 v[14:17], v3 offset:52224
	ds_read_b128 v[222:225], v3 offset:52256
	s_waitcnt lgkmcnt(1)
	v_mfma_f32_32x32x16_bf16 v[34:49], v[14:17], v[6:9], v[34:49]
	ds_read_b128 v[14:17], v226
	ds_read_b128 v[226:229], v226 offset:32
	s_waitcnt lgkmcnt(1)
	v_mfma_f32_32x32x16_bf16 v[18:33], v[14:17], v[6:9], v[18:33]
	s_waitcnt vmcnt(2)
	v_mfma_f32_32x32x16_bf16 v[130:145], v[198:201], v[10:13], v[130:145]
	v_mfma_f32_32x32x16_bf16 v[114:129], v[202:205], v[10:13], v[114:129]
	v_mfma_f32_32x32x16_bf16 v[98:113], v[206:209], v[10:13], v[98:113]
	v_mfma_f32_32x32x16_bf16 v[82:97], v[210:213], v[10:13], v[82:97]
	v_mfma_f32_32x32x16_bf16 v[66:81], v[214:217], v[10:13], v[66:81]
	v_mfma_f32_32x32x16_bf16 v[50:65], v[218:221], v[10:13], v[50:65]
	v_mfma_f32_32x32x16_bf16 v[34:49], v[222:225], v[10:13], v[34:49]
	s_waitcnt lgkmcnt(0)
	v_mfma_f32_32x32x16_bf16 v[18:33], v[226:229], v[10:13], v[18:33]
	s_mov_b32 s6, 64
	global_load_dwordx4 v[6:9], v[4:5], off offset:96
	global_load_dwordx4 v[10:13], v[4:5], off offset:128
	v_add_u32_e32 v3, s6, v195
	ds_read_b128 v[14:17], v3
	ds_read_b128 v[198:201], v3 offset:32
	v_add_u32_e32 v185, s6, v194
	v_add_u32_e32 v210, s6, v193
	v_add_u32_e32 v218, s6, v192
	v_add_u32_e32 v226, s6, v191
	s_waitcnt vmcnt(3) lgkmcnt(1)
	v_mfma_f32_32x32x16_bf16 v[130:145], v[14:17], v[230:233], v[130:145]
	ds_read_b128 v[14:17], v185
	ds_read_b128 v[202:205], v185 offset:32
	s_waitcnt lgkmcnt(1)
	v_mfma_f32_32x32x16_bf16 v[114:129], v[14:17], v[230:233], v[114:129]
	ds_read_b128 v[14:17], v3 offset:17408
	ds_read_b128 v[206:209], v3 offset:17440
	s_waitcnt lgkmcnt(1)
	v_mfma_f32_32x32x16_bf16 v[98:113], v[14:17], v[230:233], v[98:113]
	ds_read_b128 v[14:17], v210
	ds_read_b128 v[210:213], v210 offset:32
	s_waitcnt lgkmcnt(1)
	v_mfma_f32_32x32x16_bf16 v[82:97], v[14:17], v[230:233], v[82:97]
	ds_read_b128 v[14:17], v3 offset:34816
	ds_read_b128 v[214:217], v3 offset:34848
	s_waitcnt lgkmcnt(1)
	v_mfma_f32_32x32x16_bf16 v[66:81], v[14:17], v[230:233], v[66:81]
	ds_read_b128 v[14:17], v218
	ds_read_b128 v[218:221], v218 offset:32
	s_waitcnt lgkmcnt(1)
	v_mfma_f32_32x32x16_bf16 v[50:65], v[14:17], v[230:233], v[50:65]
	ds_read_b128 v[14:17], v3 offset:52224
	ds_read_b128 v[222:225], v3 offset:52256
	s_waitcnt lgkmcnt(1)
	v_mfma_f32_32x32x16_bf16 v[34:49], v[14:17], v[230:233], v[34:49]
	ds_read_b128 v[14:17], v226
	ds_read_b128 v[226:229], v226 offset:32
	s_waitcnt lgkmcnt(1)
	v_mfma_f32_32x32x16_bf16 v[18:33], v[14:17], v[230:233], v[18:33]
	s_waitcnt vmcnt(2)
	v_mfma_f32_32x32x16_bf16 v[130:145], v[198:201], v[234:237], v[130:145]
	v_mfma_f32_32x32x16_bf16 v[114:129], v[202:205], v[234:237], v[114:129]
	v_mfma_f32_32x32x16_bf16 v[98:113], v[206:209], v[234:237], v[98:113]
	v_mfma_f32_32x32x16_bf16 v[82:97], v[210:213], v[234:237], v[82:97]
	v_mfma_f32_32x32x16_bf16 v[66:81], v[214:217], v[234:237], v[66:81]
	v_mfma_f32_32x32x16_bf16 v[50:65], v[218:221], v[234:237], v[50:65]
	v_mfma_f32_32x32x16_bf16 v[34:49], v[222:225], v[234:237], v[34:49]
	s_waitcnt lgkmcnt(0)
; #define LAS __attribute__((address_space(3)))
; #define MFMA32(a, b, c) __builtin_amdgcn_mfma_f32_32x32x16_bf16((a), (b), (c), 0, 0, 0)
; __device__ __forceinline__ void xa_item(int it, LAS unsigned char* lds, const bf16_t* XQ, const bf16_t* XK, bf16_t* PB, int tid, int wid, int lane) {
;     ...
;         if (wid < 4) {
; #pragma unroll 2
;             for (int ks = 0; ks < 8; ++ks) {
;                 const bf16x8 qv = *(const bf16x8*)(qp + c * 128 + 16 * ks);
; #pragma unroll
;                 for (int mt = 0; mt < 8; ++mt) st[mt] = MFMA32(*(const LAS bf16x8*)(KL + (32 * mt + x) * KS + 16 * ks + 8 * hi), qv, st[mt]);
;             }
;         }
	v_mfma_f32_32x32x16_bf16 v[18:33], v[226:229], v[234:237], v[18:33]
	s_mov_b32 s6, 128
	global_load_dwordx4 v[230:233], v[4:5], off offset:160
	global_load_dwordx4 v[234:237], v[4:5], off offset:192
	v_add_u32_e32 v3, s6, v195
	ds_read_b128 v[14:17], v3
	ds_read_b128 v[198:201], v3 offset:32
	v_add_u32_e32 v185, s6, v194
	v_add_u32_e32 v210, s6, v193
	v_add_u32_e32 v218, s6, v192
	v_add_u32_e32 v226, s6, v191
	s_waitcnt vmcnt(3) lgkmcnt(1)
	v_mfma_f32_32x32x16_bf16 v[130:145], v[14:17], v[6:9], v[130:145]
	ds_read_b128 v[14:17], v185
	ds_read_b128 v[202:205], v185 offset:32
	s_waitcnt lgkmcnt(1)
	v_mfma_f32_32x32x16_bf16 v[114:129], v[14:17], v[6:9], v[114:129]
	ds_read_b128 v[14:17], v3 offset:17408
	ds_read_b128 v[206:209], v3 offset:17440
	s_waitcnt lgkmcnt(1)
	v_mfma_f32_32x32x16_bf16 v[98:113], v[14:17], v[6:9], v[98:113]
	ds_read_b128 v[14:17], v210
	ds_read_b128 v[210:213], v210 offset:32
	s_waitcnt lgkmcnt(1)
	v_mfma_f32_32x32x16_bf16 v[82:97], v[14:17], v[6:9], v[82:97]
	ds_read_b128 v[14:17], v3 offset:34816
	ds_read_b128 v[214:217], v3 offset:34848
	s_waitcnt lgkmcnt(1)
	v_mfma_f32_32x32x16_bf16 v[66:81], v[14:17], v[6:9], v[66:81]
	ds_read_b128 v[14:17], v218
	ds_read_b128 v[218:221], v218 offset:32
	s_waitcnt lgkmcnt(1)
	v_mfma_f32_32x32x16_bf16 v[50:65], v[14:17], v[6:9], v[50:65]
	ds_read_b128 v[14:17], v3 offset:52224
	ds_read_b128 v[222:225], v3 offset:52256
	s_waitcnt lgkmcnt(1)
	v_mfma_f32_32x32x16_bf16 v[34:49], v[14:17], v[6:9], v[34:49]
	ds_read_b128 v[14:17], v226
	ds_read_b128 v[226:229], v226 offset:32
	s_waitcnt lgkmcnt(1)
	v_mfma_f32_32x32x16_bf16 v[18:33], v[14:17], v[6:9], v[18:33]
	s_waitcnt vmcnt(2)
	v_mfma_f32_32x32x16_bf16 v[130:145], v[198:201], v[10:13], v[130:145]
	v_mfma_f32_32x32x16_bf16 v[114:129], v[202:205], v[10:13], v[114:129]
	v_mfma_f32_32x32x16_bf16 v[98:113], v[206:209], v[10:13], v[98:113]
	v_mfma_f32_32x32x16_bf16 v[82:97], v[210:213], v[10:13], v[82:97]
	v_mfma_f32_32x32x16_bf16 v[66:81], v[214:217], v[10:13], v[66:81]
	v_mfma_f32_32x32x16_bf16 v[50:65], v[218:221], v[10:13], v[50:65]
	v_mfma_f32_32x32x16_bf16 v[34:49], v[222:225], v[10:13], v[34:49]
	s_waitcnt lgkmcnt(0)
	v_mfma_f32_32x32x16_bf16 v[18:33], v[226:229], v[10:13], v[18:33]
	s_mov_b32 s6, 192
	v_add_u32_e32 v3, s6, v195
	ds_read_b128 v[14:17], v3
	ds_read_b128 v[198:201], v3 offset:32
	v_add_u32_e32 v185, s6, v194
	v_add_u32_e32 v210, s6, v193
	v_add_u32_e32 v218, s6, v192
	v_add_u32_e32 v226, s6, v191
	s_waitcnt vmcnt(1) lgkmcnt(1)
	v_mfma_f32_32x32x16_bf16 v[130:145], v[14:17], v[230:233], v[130:145]
	ds_read_b128 v[14:17], v185
	ds_read_b128 v[202:205], v185 offset:32
	s_waitcnt lgkmcnt(1)
	v_mfma_f32_32x32x16_bf16 v[114:129], v[14:17], v[230:233], v[114:129]
	ds_read_b128 v[14:17], v3 offset:17408
	ds_read_b128 v[206:209], v3 offset:17440
	s_waitcnt lgkmcnt(1)
	v_mfma_f32_32x32x16_bf16 v[98:113], v[14:17], v[230:233], v[98:113]
	ds_read_b128 v[14:17], v210
	ds_read_b128 v[210:213], v210 offset:32
	s_waitcnt lgkmcnt(1)
	v_mfma_f32_32x32x16_bf16 v[82:97], v[14:17], v[230:233], v[82:97]
	ds_read_b128 v[14:17], v3 offset:34816
	ds_read_b128 v[214:217], v3 offset:34848
	s_waitcnt lgkmcnt(1)
	v_mfma_f32_32x32x16_bf16 v[66:81], v[14:17], v[230:233], v[66:81]
	ds_read_b128 v[14:17], v218
	ds_read_b128 v[218:221], v218 offset:32
	s_waitcnt lgkmcnt(1)
	v_mfma_f32_32x32x16_bf16 v[50:65], v[14:17], v[230:233], v[50:65]
	ds_read_b128 v[14:17], v3 offset:52224
	ds_read_b128 v[222:225], v3 offset:52256
	s_waitcnt lgkmcnt(1)
	v_mfma_f32_32x32x16_bf16 v[34:49], v[14:17], v[230:233], v[34:49]
	ds_read_b128 v[14:17], v226
	ds_read_b128 v[226:229], v226 offset:32
	s_waitcnt lgkmcnt(1)
	v_mfma_f32_32x32x16_bf16 v[18:33], v[14:17], v[230:233], v[18:33]
	s_waitcnt vmcnt(0)
	v_mfma_f32_32x32x16_bf16 v[130:145], v[198:201], v[234:237], v[130:145]
	v_mfma_f32_32x32x16_bf16 v[114:129], v[202:205], v[234:237], v[114:129]
	v_mfma_f32_32x32x16_bf16 v[98:113], v[206:209], v[234:237], v[98:113]
	v_mfma_f32_32x32x16_bf16 v[82:97], v[210:213], v[234:237], v[82:97]
	v_mfma_f32_32x32x16_bf16 v[66:81], v[214:217], v[234:237], v[66:81]
	v_mfma_f32_32x32x16_bf16 v[50:65], v[218:221], v[234:237], v[50:65]
	v_mfma_f32_32x32x16_bf16 v[34:49], v[222:225], v[234:237], v[34:49]
	s_waitcnt lgkmcnt(0)
	v_mfma_f32_32x32x16_bf16 v[18:33], v[226:229], v[234:237], v[18:33]
	s_branch .LBB0_1512
